# P6 (sample-row split-K reduction) rewritten: quarter rows on every wave of the grid, all loads issued at once
# speedup vs baseline: 1.0660x; 1.0053x over previous
; __device__ __forceinline__ int ltid() { int t = threadIdx.x; asm volatile("" : "+v"(t)); return t; }
; __device__ __forceinline__ unsigned pk2(float lo, float hi) { unsigned r; asm("v_cvt_pk_bf16_f32 %0, %1, %2" : "=v"(r) : "v"(lo), "v"(hi)); return r; }
; __device__ __forceinline__ KArgs ka_get() { KArgs p = (KArgs)__builtin_amdgcn_kernarg_segment_ptr(); asm volatile("" : "+s"(p)); return p; }
; __global__ void __launch_bounds__(512, 2) mk_fwd(Args args) {
;     ...
;     if (IN(6)) { const KArgs KA = ka_get(); const int tid = ltid(), lane = tid & 63, wave = __builtin_amdgcn_readfirstlane(tid >> 6); (void)lane; (void)wave;
;         float* SSQ1 = (float*)(ws + WS_CTL + CTL_SSQ1);
;         for (int m = MP + bx * 8 + wave; m < MT; m += G * 8) {
;             const float* base = x_sample + (size_t)(m - MP) * DM; const float* part = PART + (size_t)(m - MP) * DM;
;             f32x4 v[8];
; #pragma unroll
;             for (int j = 0; j < 8; ++j) v[j] = *(const f32x4*)(base + (j * 64 + lane) * 4);
;             for (int sp = 0; sp < S2; ++sp) {
; #pragma unroll
;                 for (int j = 0; j < 8; ++j) v[j] += *(const f32x4*)(part + (size_t)sp * MS * DM + (j * 64 + lane) * 4); }
;             float sq = 0.f;
; #pragma unroll
;             for (int j = 0; j < 8; ++j) sq += (v[j].x * v[j].x + v[j].y * v[j].y) + (v[j].z * v[j].z + v[j].w * v[j].w);
;             sq = wave_sum(sq);
;             if (lane == 0) SSQ1[m] = sq;
; #pragma unroll
;             for (int j = 0; j < 8; ++j) { u32x2 o; o.x = pk2(v[j].x, v[j].y); o.y = pk2(v[j].z, v[j].w); *(u32x2*)(XN + (size_t)m * DM + (j * 64 + lane) * 4) = o; }
;         }
.LBB0_729:
	s_cmp_lt_i32 s88, 7
	s_cselect_b64 s[4:5], -1, 0
	s_and_b64 s[0:1], s[4:5], s[0:1]
	s_andn2_b64 vcc, exec, s[0:1]
	s_cbranch_vccnz .LBB0_735
	s_waitcnt vmcnt(0)
	v_readfirstlane_b32 s3, v212
	s_load_dwordx2 s[10:11], s[96:97], 0xd0
	s_load_dwordx2 s[12:13], s[96:97], 0x8
	s_lshl_b32 s6, s2, 3
	s_lshr_b32 s3, s3, 6
	s_add_u32 s6, s6, s3
	s_cmpk_gt_u32 s6, 2047
	s_cbranch_scc1 .Lp6_done
	s_lshr_b32 s7, s6, 2
	s_and_b32 s8, s6, 3
	v_and_b32_e32 v0, 63, v212
	v_lshlrev_b32_e32 v1, 5, v0
	v_lshlrev_b32_e32 v2, 4, v0
	v_xor_b32_e32 v100, 1, v0
	v_lshlrev_b32_e32 v100, 2, v100
	v_xor_b32_e32 v101, 2, v0
	v_lshlrev_b32_e32 v101, 2, v101
	v_xor_b32_e32 v102, 4, v0
	v_lshlrev_b32_e32 v102, 2, v102
	v_xor_b32_e32 v103, 8, v0
	v_lshlrev_b32_e32 v103, 2, v103
	v_xor_b32_e32 v104, 16, v0
	v_lshlrev_b32_e32 v104, 2, v104
	v_xor_b32_e32 v105, 32, v0
	v_lshlrev_b32_e32 v105, 2, v105
	s_lshl_b32 s14, s7, 13
	s_lshl_b32 s9, s8, 11
	s_add_u32 s14, s14, s9
	s_waitcnt lgkmcnt(0)
	s_add_u32 s16, s12, s14
	s_addc_u32 s17, s13, 0
	s_add_u32 s18, s10, 0x9890000
	s_addc_u32 s19, s11, 0
	s_add_u32 s18, s18, s14
	s_addc_u32 s19, s19, 0
	global_load_dwordx4 v[8:11], v1, s[16:17]
	global_load_dwordx4 v[12:15], v1, s[16:17] offset:16
	global_load_dwordx4 v[16:19], v1, s[18:19]
	global_load_dwordx4 v[20:23], v1, s[18:19] offset:16
	s_add_u32 s18, s18, 0x400000
	s_addc_u32 s19, s19, 0
	global_load_dwordx4 v[24:27], v1, s[18:19]
	global_load_dwordx4 v[28:31], v1, s[18:19] offset:16
	s_add_u32 s18, s18, 0x400000
	s_addc_u32 s19, s19, 0
	global_load_dwordx4 v[32:35], v1, s[18:19]
	global_load_dwordx4 v[36:39], v1, s[18:19] offset:16
	s_add_u32 s18, s18, 0x400000
	s_addc_u32 s19, s19, 0
	global_load_dwordx4 v[40:43], v1, s[18:19]
	global_load_dwordx4 v[44:47], v1, s[18:19] offset:16
	s_add_u32 s18, s18, 0x400000
	s_addc_u32 s19, s19, 0
	global_load_dwordx4 v[48:51], v1, s[18:19]
	global_load_dwordx4 v[52:55], v1, s[18:19] offset:16
	s_add_u32 s18, s18, 0x400000
	s_addc_u32 s19, s19, 0
	global_load_dwordx4 v[56:59], v1, s[18:19]
	global_load_dwordx4 v[60:63], v1, s[18:19] offset:16
	s_add_u32 s18, s18, 0x400000
	s_addc_u32 s19, s19, 0
	global_load_dwordx4 v[64:67], v1, s[18:19]
	global_load_dwordx4 v[68:71], v1, s[18:19] offset:16
	s_add_u32 s18, s18, 0x400000
	s_addc_u32 s19, s19, 0
	global_load_dwordx4 v[72:75], v1, s[18:19]
	global_load_dwordx4 v[76:79], v1, s[18:19] offset:16
	s_add_u32 s20, s7, 8192
	s_lshl_b32 s21, s20, 12
	s_lshl_b32 s9, s8, 10
	s_add_u32 s21, s21, s9
	s_add_u32 s22, s10, 0x7580000
	s_addc_u32 s23, s11, 0
	s_add_u32 s22, s22, s21
	s_addc_u32 s23, s23, 0
	s_lshl_b32 s21, s20, 2
	s_add_u32 s24, s10, 0x1f0e0000
	s_addc_u32 s25, s11, 0
	s_add_u32 s24, s24, s21
	s_addc_u32 s25, s25, 0
	s_waitcnt vmcnt(14)
	v_add_f32_e32 v8, v8, v16
	v_add_f32_e32 v9, v9, v17
	v_add_f32_e32 v10, v10, v18
	v_add_f32_e32 v11, v11, v19
	v_add_f32_e32 v12, v12, v20
	v_add_f32_e32 v13, v13, v21
	v_add_f32_e32 v14, v14, v22
	v_add_f32_e32 v15, v15, v23
	s_waitcnt vmcnt(12)
	v_add_f32_e32 v8, v8, v24
	v_add_f32_e32 v9, v9, v25
	v_add_f32_e32 v10, v10, v26
	v_add_f32_e32 v11, v11, v27
	v_add_f32_e32 v12, v12, v28
	v_add_f32_e32 v13, v13, v29
	v_add_f32_e32 v14, v14, v30
	v_add_f32_e32 v15, v15, v31
	s_waitcnt vmcnt(10)
	v_add_f32_e32 v8, v8, v32
	v_add_f32_e32 v9, v9, v33
	v_add_f32_e32 v10, v10, v34
	v_add_f32_e32 v11, v11, v35
	v_add_f32_e32 v12, v12, v36
	v_add_f32_e32 v13, v13, v37
	v_add_f32_e32 v14, v14, v38
	v_add_f32_e32 v15, v15, v39
	s_waitcnt vmcnt(8)
	v_add_f32_e32 v8, v8, v40
	v_add_f32_e32 v9, v9, v41
	v_add_f32_e32 v10, v10, v42
	v_add_f32_e32 v11, v11, v43
	v_add_f32_e32 v12, v12, v44
	v_add_f32_e32 v13, v13, v45
	v_add_f32_e32 v14, v14, v46
	v_add_f32_e32 v15, v15, v47
	s_waitcnt vmcnt(6)
	v_add_f32_e32 v8, v8, v48
	v_add_f32_e32 v9, v9, v49
	v_add_f32_e32 v10, v10, v50
	v_add_f32_e32 v11, v11, v51
	v_add_f32_e32 v12, v12, v52
	v_add_f32_e32 v13, v13, v53
	v_add_f32_e32 v14, v14, v54
	v_add_f32_e32 v15, v15, v55
	s_waitcnt vmcnt(4)
	v_add_f32_e32 v8, v8, v56
	v_add_f32_e32 v9, v9, v57
	v_add_f32_e32 v10, v10, v58
	v_add_f32_e32 v11, v11, v59
	v_add_f32_e32 v12, v12, v60
	v_add_f32_e32 v13, v13, v61
	v_add_f32_e32 v14, v14, v62
	v_add_f32_e32 v15, v15, v63
	s_waitcnt vmcnt(2)
	v_add_f32_e32 v8, v8, v64
	v_add_f32_e32 v9, v9, v65
	v_add_f32_e32 v10, v10, v66
	v_add_f32_e32 v11, v11, v67
	v_add_f32_e32 v12, v12, v68
	v_add_f32_e32 v13, v13, v69
	v_add_f32_e32 v14, v14, v70
	v_add_f32_e32 v15, v15, v71
	s_waitcnt vmcnt(0)
	v_add_f32_e32 v8, v8, v72
	v_add_f32_e32 v9, v9, v73
	v_add_f32_e32 v10, v10, v74
	v_add_f32_e32 v11, v11, v75
	v_add_f32_e32 v12, v12, v76
	v_add_f32_e32 v13, v13, v77
	v_add_f32_e32 v14, v14, v78
	v_add_f32_e32 v15, v15, v79
	v_mul_f32_e32 v80, v8, v8
	v_mul_f32_e32 v81, v10, v10
	v_mul_f32_e32 v82, v12, v12
	v_mul_f32_e32 v83, v14, v14
	v_fmac_f32_e32 v80, v9, v9
	v_fmac_f32_e32 v81, v11, v11
	v_fmac_f32_e32 v82, v13, v13
	v_fmac_f32_e32 v83, v15, v15
	v_add_f32_e32 v80, v80, v81
	v_add_f32_e32 v82, v82, v83
	v_add_f32_e32 v80, v80, v82
	ds_bpermute_b32 v81, v100, v80
	s_waitcnt lgkmcnt(0)
	v_add_f32_e32 v80, v80, v81
	ds_bpermute_b32 v81, v101, v80
	s_waitcnt lgkmcnt(0)
	v_add_f32_e32 v80, v80, v81
	ds_bpermute_b32 v81, v102, v80
	s_waitcnt lgkmcnt(0)
	v_add_f32_e32 v80, v80, v81
	ds_bpermute_b32 v81, v103, v80
	s_waitcnt lgkmcnt(0)
	v_add_f32_e32 v80, v80, v81
	ds_bpermute_b32 v81, v104, v80
	s_waitcnt lgkmcnt(0)
	v_add_f32_e32 v80, v80, v81
	ds_bpermute_b32 v81, v105, v80
	s_waitcnt lgkmcnt(0)
	v_add_f32_e32 v80, v80, v81
	v_cvt_pk_bf16_f32 v84, v8, v9
	v_cvt_pk_bf16_f32 v85, v10, v11
	v_cvt_pk_bf16_f32 v86, v12, v13
	v_cvt_pk_bf16_f32 v87, v14, v15
	global_store_dwordx4 v2, v[84:87], s[22:23]
	v_mov_b32_e32 v3, 0
	s_mov_b64 s[26:27], exec
	s_mov_b64 exec, 1
	global_atomic_add_f32 v3, v80, s[24:25]
	s_mov_b64 exec, s[26:27]
.Lp6_done:
.LBB0_735:
	s_cmp_gt_i32 s89, 7
	s_cselect_b64 s[4:5], -1, 0
	s_and_b64 s[0:1], s[0:1], s[4:5]
	s_andn2_b64 vcc, exec, s[0:1]
	s_cbranch_vccnz .LBB0_789
	s_waitcnt vmcnt(0)
	s_waitcnt vmcnt(0) lgkmcnt(0)
	s_barrier
	s_and_saveexec_b64 s[0:1], s[90:91]
	s_cbranch_execz .LBB0_788
	s_add_i32 s3, 0, 0x23fc0
	v_mov_b32_e32 v0, s3
	s_waitcnt vmcnt(0) expcnt(0) lgkmcnt(0)
	ds_read_b32 v2, v0
	s_add_i32 s3, 0, 0x23fc4
	v_mov_b32_e32 v0, s3
	ds_read_b32 v0, v0
	s_waitcnt lgkmcnt(1)
	v_cmp_ne_u32_e32 vcc, 0, v2
	s_cbranch_vccnz .LBB0_752
	v_readlane_b32 s6, v253, 0
	v_readlane_b32 s7, v253, 1
	s_load_dwordx2 s[10:11], s[6:7], 0x4
	s_add_u32 s6, s74, 0x1000
	s_addc_u32 s7, s75, 0
	s_add_u32 s8, s74, 0x1100
	s_addc_u32 s9, s75, 0
	s_waitcnt lgkmcnt(0)
	s_mul_i32 s3, s10, s94
	s_add_u32 s10, s74, 0x1200
	s_mul_i32 s3, s3, s11
	s_addc_u32 s11, s75, 0
	s_add_u32 s12, s74, 0x1300
	s_addc_u32 s13, s75, 0
	s_mov_b32 s20, 1
	v_mov_b32_e32 v16, 0
	s_branch .LBB0_740
